# same stack as v036 but attention rescale as 64 single v_mul_f32 (no packed v_pk_mul_f32 between the PV MFMAs)
# speedup vs baseline: 1.0083x; 1.0011x over previous
.LBB0_323:
	s_and_saveexec_b64 s[72:73], s[6:7]
	s_cbranch_execz .LBB0_310
	ds_read_b128 v[220:223], v245
	ds_read_b128 v[224:227], v245 offset:32
	ds_read_b128 v[2:5], v245 offset:64
	ds_read_b128 v[6:9], v245 offset:96
	s_waitcnt lgkmcnt(3)
	v_mfma_f32_32x32x16_bf16 v[96:111], v[220:223], v[172:175], 0
	ds_read_b128 v[220:223], v245 offset:128
	s_waitcnt lgkmcnt(3)
	v_mfma_f32_32x32x16_bf16 v[96:111], v[224:227], v[168:171], v[96:111]
	ds_read_b128 v[224:227], v245 offset:160
	s_waitcnt lgkmcnt(3)
	v_mfma_f32_32x32x16_bf16 v[96:111], v[2:5], v[164:167], v[96:111]
	ds_read_b128 v[2:5], v245 offset:192
	s_waitcnt lgkmcnt(3)
	v_mfma_f32_32x32x16_bf16 v[96:111], v[6:9], v[160:163], v[96:111]
	ds_read_b128 v[6:9], v245 offset:224
	s_waitcnt lgkmcnt(3)
	v_mfma_f32_32x32x16_bf16 v[96:111], v[220:223], v[156:159], v[96:111]
	ds_read_b128 v[220:223], v245 offset:256
	s_waitcnt lgkmcnt(3)
	v_mfma_f32_32x32x16_bf16 v[96:111], v[224:227], v[152:155], v[96:111]
	ds_read_b128 v[224:227], v245 offset:288
	s_waitcnt lgkmcnt(3)
	v_mfma_f32_32x32x16_bf16 v[96:111], v[2:5], v[148:151], v[96:111]
	ds_read_b128 v[2:5], v245 offset:320
	s_waitcnt lgkmcnt(3)
	v_mfma_f32_32x32x16_bf16 v[96:111], v[6:9], v[144:147], v[96:111]
	ds_read_b128 v[6:9], v245 offset:352
	s_waitcnt lgkmcnt(3)
	v_mfma_f32_32x32x16_bf16 v[96:111], v[220:223], v[140:143], v[96:111]
	ds_read_b128 v[220:223], v245 offset:384
	s_waitcnt lgkmcnt(3)
	v_mfma_f32_32x32x16_bf16 v[96:111], v[224:227], v[136:139], v[96:111]
	ds_read_b128 v[224:227], v245 offset:416
	s_waitcnt lgkmcnt(3)
	v_mfma_f32_32x32x16_bf16 v[96:111], v[2:5], v[132:135], v[96:111]
	ds_read_b128 v[2:5], v245 offset:448
	s_waitcnt lgkmcnt(3)
	v_mfma_f32_32x32x16_bf16 v[96:111], v[6:9], v[128:131], v[96:111]
	ds_read_b128 v[6:9], v245 offset:480
	s_waitcnt lgkmcnt(3)
	v_mfma_f32_32x32x16_bf16 v[96:111], v[220:223], v[124:127], v[96:111]
	ds_read_b128 v[220:223], v245 offset:16896
	s_waitcnt lgkmcnt(3)
	v_mfma_f32_32x32x16_bf16 v[96:111], v[224:227], v[120:123], v[96:111]
	ds_read_b128 v[224:227], v245 offset:16928
	s_waitcnt lgkmcnt(3)
	v_mfma_f32_32x32x16_bf16 v[96:111], v[2:5], v[116:119], v[96:111]
	ds_read_b128 v[2:5], v245 offset:16960
	s_waitcnt lgkmcnt(3)
	v_mfma_f32_32x32x16_bf16 v[96:111], v[6:9], v[112:115], v[96:111]
	ds_read_b128 v[6:9], v245 offset:16992
	s_waitcnt lgkmcnt(3)
	v_mfma_f32_32x32x16_bf16 v[80:95], v[220:223], v[172:175], 0
	ds_read_b128 v[220:223], v245 offset:17024
	s_waitcnt lgkmcnt(3)
	v_mfma_f32_32x32x16_bf16 v[80:95], v[224:227], v[168:171], v[80:95]
	ds_read_b128 v[224:227], v245 offset:17056
	s_waitcnt lgkmcnt(3)
	v_mfma_f32_32x32x16_bf16 v[80:95], v[2:5], v[164:167], v[80:95]
	ds_read_b128 v[2:5], v245 offset:17088
	s_waitcnt lgkmcnt(3)
	v_mfma_f32_32x32x16_bf16 v[80:95], v[6:9], v[160:163], v[80:95]
	ds_read_b128 v[6:9], v245 offset:17120
	s_waitcnt lgkmcnt(3)
	v_mfma_f32_32x32x16_bf16 v[80:95], v[220:223], v[156:159], v[80:95]
	ds_read_b128 v[220:223], v245 offset:17152
	s_waitcnt lgkmcnt(3)
	v_mfma_f32_32x32x16_bf16 v[80:95], v[224:227], v[152:155], v[80:95]
	ds_read_b128 v[224:227], v245 offset:17184
	s_waitcnt lgkmcnt(3)
	v_mfma_f32_32x32x16_bf16 v[80:95], v[2:5], v[148:151], v[80:95]
	ds_read_b128 v[2:5], v245 offset:17216
	s_waitcnt lgkmcnt(3)
	v_mfma_f32_32x32x16_bf16 v[80:95], v[6:9], v[144:147], v[80:95]
	ds_read_b128 v[6:9], v245 offset:17248
	s_waitcnt lgkmcnt(3)
	v_mfma_f32_32x32x16_bf16 v[80:95], v[220:223], v[140:143], v[80:95]
	ds_read_b128 v[220:223], v245 offset:17280
	s_waitcnt lgkmcnt(3)
	v_mfma_f32_32x32x16_bf16 v[80:95], v[224:227], v[136:139], v[80:95]
	ds_read_b128 v[224:227], v245 offset:17312
	s_waitcnt lgkmcnt(3)
	v_mfma_f32_32x32x16_bf16 v[80:95], v[2:5], v[132:135], v[80:95]
	ds_read_b128 v[2:5], v245 offset:17344
	s_waitcnt lgkmcnt(3)
	v_mfma_f32_32x32x16_bf16 v[80:95], v[6:9], v[128:131], v[80:95]
	ds_read_b128 v[6:9], v245 offset:17376
	s_waitcnt lgkmcnt(3)
	v_mfma_f32_32x32x16_bf16 v[80:95], v[220:223], v[124:127], v[80:95]
	s_waitcnt lgkmcnt(2)
	v_mfma_f32_32x32x16_bf16 v[80:95], v[224:227], v[120:123], v[80:95]
	s_waitcnt lgkmcnt(1)
	v_mfma_f32_32x32x16_bf16 v[80:95], v[2:5], v[116:119], v[80:95]
	s_waitcnt lgkmcnt(0)
	v_mfma_f32_32x32x16_bf16 v[80:95], v[6:9], v[112:115], v[80:95]
	v_max_f32_e32 v0, v97, v97
	v_max_f32_e32 v10, v96, v96
	v_max_f32_e32 v0, v10, v0
	v_max3_f32 v0, v0, v98, v99
	v_max3_f32 v0, v0, v100, v101
	v_max3_f32 v0, v0, v102, v103
	v_max3_f32 v0, v0, v104, v105
	v_max3_f32 v0, v0, v106, v107
	v_max3_f32 v0, v0, v108, v109
	v_max3_f32 v0, v0, v110, v111
	v_and_b32_e32 v3, 64, v218
	v_xor_b32_e32 v2, 32, v218
	v_add_u32_e32 v3, 64, v3
	v_cmp_lt_i32_e32 vcc, v2, v3
	s_nop 1
	v_cndmask_b32_e32 v2, v218, v2, vcc
	v_lshlrev_b32_e32 v2, 2, v2
	s_nop 10
	v_max3_f32 v0, v0, v80, v81
	v_max3_f32 v0, v0, v82, v83
	v_max3_f32 v0, v0, v84, v85
	v_max3_f32 v0, v0, v86, v87
	v_max3_f32 v0, v0, v88, v89
	v_max3_f32 v0, v0, v90, v91
	v_max3_f32 v0, v0, v92, v93
	v_max3_f32 v0, v0, v94, v95
	v_mov_b32_e32 v2, v0
	s_nop 1
	v_permlane32_swap_b32_e32 v2, v0
	s_nop 1
	v_max3_f32 v0, v236, v0, v2
	v_sub_f32 v4, v97, v0
	v_sub_f32 v3, v96, v0
	v_sub_f32 v5, v100, v0
	v_sub_f32_e32 v2, v236, v0
	v_exp_f32_e32 v8, v4
	v_sub_f32 v4, v98, v0
	v_exp_f32_e32 v3, v3
	v_exp_f32_e32 v9, v4
	v_sub_f32 v4, v99, v0
	v_exp_f32_e32 v11, v5
	v_exp_f32_e32 v10, v4
	v_add_f32 v4, v1, v3
	v_sub_f32 v5, v101, v0
	v_exp_f32_e32 v2, v2
	v_add_f32 v4, v4, v8
	v_exp_f32_e32 v12, v5
	v_add_f32 v4, v4, v9
	v_sub_f32 v5, v102, v0
	v_cvt_pk_bf16_f32 v8, v3, v8
	v_add_f32 v4, v4, v10
	v_exp_f32_e32 v13, v5
	v_add_f32 v4, v4, v11
	v_sub_f32 v5, v103, v0
	v_add_u32_e32 v3, 0x9000, v219
	v_add_f32 v4, v4, v12
	v_exp_f32_e32 v14, v5
	v_add_f32 v4, v4, v13
	v_cvt_pk_bf16_f32 v9, v9, v10
	v_add_f32 v96, v4, v14
	v_sub_f32 v4, v104, v0
	v_add_u32_e32 v104, 0x8000, v219
	v_exp_f32_e32 v97, v4
	v_sub_f32 v4, v105, v0
	v_cvt_pk_bf16_f32 v10, v11, v12
	v_exp_f32_e32 v98, v4
	v_sub_f32 v4, v106, v0
	v_cvt_pk_bf16_f32 v11, v13, v14
	v_exp_f32_e32 v99, v4
	v_sub_f32 v4, v107, v0
	ds_read2_b64 v[12:15], v3 offset0:160 offset1:162
	v_exp_f32_e32 v100, v4
	v_sub_f32 v4, v108, v0
	v_mul_f32 v64, v64, v2
	v_mul_f32 v65, v65, v2
	v_mul_f32 v66, v66, v2
	v_mul_f32 v67, v67, v2
	v_mul_f32 v68, v68, v2
	s_nop 0
	v_exp_f32_e32 v101, v4
	v_sub_f32 v4, v109, v0
	v_mul_f32 v69, v69, v2
	v_mul_f32 v70, v70, v2
	v_mul_f32 v71, v71, v2
	v_mul_f32 v72, v72, v2
	v_mul_f32 v73, v73, v2
	s_nop 0
	v_exp_f32_e32 v102, v4
	v_sub_f32 v4, v110, v0
	v_mul_f32 v74, v74, v2
	v_mul_f32 v75, v75, v2
	v_mul_f32 v76, v76, v2
	v_mul_f32 v77, v77, v2
	v_mul_f32 v78, v78, v2
	s_nop 0
	v_exp_f32_e32 v103, v4
	ds_read2_b64 v[4:7], v104 offset0:128 offset1:130
	v_mul_f32 v79, v79, v2
	v_add_u32_e32 v105, 0xa000, v219
	s_waitcnt lgkmcnt(0)
	v_mfma_f32_32x32x16_bf16 v[64:79], v[4:7], v[8:11], v[64:79]
	ds_read2_b64 v[4:7], v105 offset0:192 offset1:194
	v_mul_f32 v48, v48, v2
	v_mul_f32 v49, v49, v2
	v_mul_f32 v50, v50, v2
	v_mul_f32 v51, v51, v2
	v_mul_f32 v52, v52, v2
	v_mul_f32 v53, v53, v2
	v_mul_f32 v54, v54, v2
	v_mul_f32 v55, v55, v2
	v_mul_f32 v56, v56, v2
	v_mul_f32 v57, v57, v2
	v_mul_f32 v58, v58, v2
	v_mul_f32 v59, v59, v2
	v_mul_f32 v60, v60, v2
	v_mul_f32 v61, v61, v2
	v_mul_f32 v62, v62, v2
	v_mul_f32 v63, v63, v2
	v_add_u32_e32 v106, 0xb000, v219
	v_mfma_f32_32x32x16_bf16 v[48:63], v[12:15], v[8:11], v[48:63]
	ds_read2_b64 v[12:15], v106 offset0:224 offset1:226
	v_mul_f32 v32, v32, v2
	v_mul_f32 v33, v33, v2
	v_mul_f32 v34, v34, v2
	v_mul_f32 v35, v35, v2
	v_mul_f32 v36, v36, v2
	v_mul_f32 v37, v37, v2
	v_mul_f32 v38, v38, v2
	v_mul_f32 v39, v39, v2
	v_mul_f32 v40, v40, v2
	v_mul_f32 v41, v41, v2
	v_mul_f32 v42, v42, v2
	v_mul_f32 v43, v43, v2
	v_mul_f32 v44, v44, v2
	v_mul_f32 v45, v45, v2
	v_mul_f32 v46, v46, v2
	v_mul_f32 v47, v47, v2
	v_mul_f32 v16, v16, v2
	v_mul_f32 v17, v17, v2
	v_mul_f32 v18, v18, v2
	v_mul_f32 v19, v19, v2
	v_mul_f32 v20, v20, v2
	s_waitcnt lgkmcnt(1)
	v_mfma_f32_32x32x16_bf16 v[32:47], v[4:7], v[8:11], v[32:47]
	ds_read2_b64 v[4:7], v104 offset0:132 offset1:134
	v_mul_f32 v21, v21, v2
	v_mul_f32 v22, v22, v2
	v_mul_f32 v23, v23, v2
	v_mul_f32 v24, v24, v2
	v_mul_f32 v25, v25, v2
	v_mul_f32 v26, v26, v2
	v_mul_f32 v27, v27, v2
	v_mul_f32 v28, v28, v2
	v_mul_f32 v29, v29, v2
	v_mul_f32 v30, v30, v2
	v_mul_f32 v31, v31, v2
	v_mov_b32_e32 v236, v0
	s_waitcnt lgkmcnt(1)
	v_mfma_f32_32x32x16_bf16 v[16:31], v[12:15], v[8:11], v[16:31]
	v_sub_f32 v8, v111, v0
	v_cvt_pk_bf16_f32 v9, v99, v100
	v_exp_f32_e32 v107, v8
	v_cvt_pk_bf16_f32 v8, v97, v98
	v_cvt_pk_bf16_f32 v10, v101, v102
	ds_read2_b64 v[12:15], v3 offset0:164 offset1:166
	v_cvt_pk_bf16_f32 v11, v103, v107
	s_waitcnt lgkmcnt(1)
	s_nop 0
	v_mfma_f32_32x32x16_bf16 v[64:79], v[4:7], v[8:11], v[64:79]
	v_add_f32 v4, v96, v97
	s_nop 0
	v_add_f32 v4, v4, v98
	s_nop 0
	v_add_f32 v4, v4, v99
	s_nop 0
	v_add_f32 v96, v4, v100
	v_sub_f32 v4, v80, v0
	s_waitcnt lgkmcnt(0)
	v_mfma_f32_32x32x16_bf16 v[48:63], v[12:15], v[8:11], v[48:63]
	v_exp_f32_e32 v80, v4
	ds_read2_b64 v[4:7], v105 offset0:196 offset1:198
	v_sub_f32 v12, v81, v0
	s_nop 0
	v_exp_f32_e32 v81, v12
	v_sub_f32 v12, v82, v0
	s_nop 0
	v_exp_f32_e32 v82, v12
	v_sub_f32 v12, v83, v0
	s_waitcnt lgkmcnt(0)
	v_mfma_f32_32x32x16_bf16 v[32:47], v[4:7], v[8:11], v[32:47]
	v_exp_f32_e32 v83, v12
	ds_read2_b64 v[12:15], v106 offset0:228 offset1:230
	v_sub_f32 v4, v84, v0
	s_nop 0
	v_exp_f32_e32 v84, v4
	v_sub_f32 v4, v85, v0
	s_nop 0
	v_exp_f32_e32 v85, v4
	v_sub_f32 v4, v86, v0
	s_waitcnt lgkmcnt(0)
	v_mfma_f32_32x32x16_bf16 v[16:31], v[12:15], v[8:11], v[16:31]
	v_exp_f32_e32 v86, v4
	ds_read2_b64 v[4:7], v104 offset0:136 offset1:138
	v_sub_f32 v8, v87, v0
	ds_read2_b64 v[12:15], v3 offset0:168 offset1:170
	v_exp_f32_e32 v87, v8
	v_cvt_pk_bf16_f32 v8, v80, v81
	v_cvt_pk_bf16_f32 v9, v82, v83
	v_cvt_pk_bf16_f32 v10, v84, v85
	v_cvt_pk_bf16_f32 v11, v86, v87
	s_waitcnt lgkmcnt(1)
	s_nop 0
	v_mfma_f32_32x32x16_bf16 v[64:79], v[4:7], v[8:11], v[64:79]
	v_add_f32 v4, v96, v101
	s_nop 0
	v_add_f32 v4, v4, v102
	s_nop 0
	v_add_f32 v4, v4, v103
	s_nop 0
	v_add_f32 v96, v4, v107
	v_sub_f32 v4, v88, v0
	s_waitcnt lgkmcnt(0)
	v_mfma_f32_32x32x16_bf16 v[48:63], v[12:15], v[8:11], v[48:63]
	v_exp_f32_e32 v88, v4
	ds_read2_b64 v[4:7], v105 offset0:200 offset1:202
	v_sub_f32 v12, v89, v0
	s_nop 0
	v_exp_f32_e32 v89, v12
	v_sub_f32 v12, v90, v0
	s_nop 0
	v_exp_f32_e32 v90, v12
	v_sub_f32 v12, v91, v0
	s_waitcnt lgkmcnt(0)
	v_mfma_f32_32x32x16_bf16 v[32:47], v[4:7], v[8:11], v[32:47]
	v_exp_f32_e32 v91, v12
	ds_read2_b64 v[12:15], v106 offset0:232 offset1:234
	v_sub_f32 v4, v92, v0
	s_nop 0
	v_exp_f32_e32 v92, v4
	v_sub_f32 v4, v93, v0
	s_nop 0
	v_exp_f32_e32 v93, v4
	v_sub_f32 v4, v94, v0
	s_waitcnt lgkmcnt(0)
	v_mfma_f32_32x32x16_bf16 v[16:31], v[12:15], v[8:11], v[16:31]
	v_exp_f32_e32 v94, v4
	ds_read2_b64 v[4:7], v104 offset0:140 offset1:142
	ds_read2_b64 v[12:15], v3 offset0:172 offset1:174
	v_sub_f32 v8, v95, v0
	v_cvt_pk_bf16_f32 v9, v90, v91
	v_exp_f32_e32 v95, v8
	v_cvt_pk_bf16_f32 v8, v88, v89
	v_cvt_pk_bf16_f32 v10, v92, v93
	v_add_f32 v3, v96, v80
	v_cvt_pk_bf16_f32 v11, v94, v95
	v_add_f32 v3, v3, v81
	s_nop 0
	v_add_f32 v3, v3, v82
	s_waitcnt lgkmcnt(1)
	v_mfma_f32_32x32x16_bf16 v[64:79], v[4:7], v[8:11], v[64:79]
	ds_read2_b64 v[4:7], v105 offset0:204 offset1:206
	v_add_f32 v3, v3, v83
	s_nop 0
	v_add_f32 v3, v3, v84
	s_nop 0
	v_add_f32 v3, v3, v85
	s_waitcnt lgkmcnt(1)
	v_mfma_f32_32x32x16_bf16 v[48:63], v[12:15], v[8:11], v[48:63]
	ds_read2_b64 v[12:15], v106 offset0:236 offset1:238
	v_add_f32 v3, v3, v86
	s_nop 0
	v_add_f32 v3, v3, v87
	s_nop 0
	v_add_f32 v3, v3, v88
	s_nop 0
	v_add_f32 v3, v3, v89
	s_waitcnt lgkmcnt(1)
	v_mfma_f32_32x32x16_bf16 v[32:47], v[4:7], v[8:11], v[32:47]
	v_add_f32 v3, v3, v90
	s_nop 0
	v_add_f32 v3, v3, v91
	s_nop 0
	v_add_f32 v3, v3, v92
	s_nop 0
	v_add_f32 v3, v3, v93
	s_waitcnt lgkmcnt(0)
	v_mfma_f32_32x32x16_bf16 v[16:31], v[12:15], v[8:11], v[16:31]
	v_add_f32 v3, v3, v94
	s_nop 0
	v_add_f32 v3, v3, v95
	s_nop 0
	v_fmac_f32_e32 v3, v246, v2
	v_mov_b32_e32 v246, v3
	s_branch .LBB0_310

.LBB0_566:
	s_and_saveexec_b64 s[22:23], vcc
	s_cbranch_execz .LBB0_555
	s_waitcnt lgkmcnt(7)
	v_mfma_f32_32x32x16_bf16 v[96:111], v[196:199], v[148:151], 0
	ds_read_b128 v[196:199], v188 offset:256
	s_waitcnt lgkmcnt(7)
	v_mfma_f32_32x32x16_bf16 v[96:111], v[202:205], v[144:147], v[96:111]
	ds_read_b128 v[202:205], v188 offset:288
	s_waitcnt lgkmcnt(7)
	v_mfma_f32_32x32x16_bf16 v[96:111], v[206:209], v[140:143], v[96:111]
	ds_read_b128 v[206:209], v188 offset:10752
	s_waitcnt lgkmcnt(7)
	v_mfma_f32_32x32x16_bf16 v[96:111], v[210:213], v[136:139], v[96:111]
	ds_read_b128 v[210:213], v188 offset:10784
	s_waitcnt lgkmcnt(7)
	v_mfma_f32_32x32x16_bf16 v[96:111], v[220:223], v[132:135], v[96:111]
	ds_read_b128 v[220:223], v188 offset:10816
	s_waitcnt lgkmcnt(7)
	v_mfma_f32_32x32x16_bf16 v[96:111], v[224:227], v[128:131], v[96:111]
	ds_read_b128 v[224:227], v188 offset:10848
	s_waitcnt lgkmcnt(7)
	v_mfma_f32_32x32x16_bf16 v[96:111], v[2:5], v[124:127], v[96:111]
	ds_read_b128 v[2:5], v188 offset:10880
	s_waitcnt lgkmcnt(7)
	v_mfma_f32_32x32x16_bf16 v[96:111], v[6:9], v[120:123], v[96:111]
	ds_read_b128 v[6:9], v188 offset:10912
	s_waitcnt lgkmcnt(7)
	v_mfma_f32_32x32x16_bf16 v[96:111], v[196:199], v[116:119], v[96:111]
	ds_read_b128 v[196:199], v188 offset:10944
	s_waitcnt lgkmcnt(7)
	v_mfma_f32_32x32x16_bf16 v[96:111], v[202:205], v[112:115], v[96:111]
	ds_read_b128 v[202:205], v188 offset:10976
	s_waitcnt lgkmcnt(7)
	v_mfma_f32_32x32x16_bf16 v[80:95], v[206:209], v[148:151], 0
	ds_read_b128 v[206:209], v188 offset:11008
	s_waitcnt lgkmcnt(7)
	v_mfma_f32_32x32x16_bf16 v[80:95], v[210:213], v[144:147], v[80:95]
	ds_read_b128 v[210:213], v188 offset:11040
	s_waitcnt lgkmcnt(7)
	v_mfma_f32_32x32x16_bf16 v[80:95], v[220:223], v[140:143], v[80:95]
	s_waitcnt lgkmcnt(6)
	v_mfma_f32_32x32x16_bf16 v[80:95], v[224:227], v[136:139], v[80:95]
	s_waitcnt lgkmcnt(5)
	v_mfma_f32_32x32x16_bf16 v[80:95], v[2:5], v[132:135], v[80:95]
	s_waitcnt lgkmcnt(4)
	v_mfma_f32_32x32x16_bf16 v[80:95], v[6:9], v[128:131], v[80:95]
	s_waitcnt lgkmcnt(3)
	v_mfma_f32_32x32x16_bf16 v[80:95], v[196:199], v[124:127], v[80:95]
	v_max_f32_e32 v0, v97, v97
	v_max_f32_e32 v10, v96, v96
	v_max_f32_e32 v0, v10, v0
	v_max3_f32 v0, v0, v98, v99
	v_max3_f32 v0, v0, v100, v101
	v_max3_f32 v0, v0, v102, v103
	v_max3_f32 v0, v0, v104, v105
	v_max3_f32 v0, v0, v106, v107
	v_max3_f32 v0, v0, v108, v109
	v_max3_f32 v0, v0, v110, v111
	v_and_b32_e32 v3, 64, v218
	v_xor_b32_e32 v2, 32, v218
	v_add_u32_e32 v3, 64, v3
	v_cmp_lt_i32_e64 s[12:13], v2, v3
	s_nop 1
	v_cndmask_b32_e64 v2, v218, v2, s[12:13]
	s_waitcnt lgkmcnt(2)
	v_mfma_f32_32x32x16_bf16 v[80:95], v[202:205], v[120:123], v[80:95]
	s_waitcnt lgkmcnt(1)
	v_mfma_f32_32x32x16_bf16 v[80:95], v[206:209], v[116:119], v[80:95]
	s_waitcnt lgkmcnt(0)
	v_mfma_f32_32x32x16_bf16 v[80:95], v[210:213], v[112:115], v[80:95]
	v_lshlrev_b32_e32 v2, 2, v2
	s_nop 10
	v_max3_f32 v0, v0, v80, v81
	v_max3_f32 v0, v0, v82, v83
	v_max3_f32 v0, v0, v84, v85
	v_max3_f32 v0, v0, v86, v87
	v_max3_f32 v0, v0, v88, v89
	v_max3_f32 v0, v0, v90, v91
	v_max3_f32 v0, v0, v92, v93
	v_max3_f32 v0, v0, v94, v95
	v_mov_b32_e32 v2, v0
	s_nop 1
	v_permlane32_swap_b32_e32 v2, v0
	s_nop 1
	v_add_u32_e32 v224, 0x5000, v194
	v_add_u32_e32 v225, 0x6000, v194
	v_add_u32_e32 v226, 0x7000, v194
	v_add_u32_e32 v227, 0x8000, v194
	ds_read2_b64 v[196:199], v224 offset0:128 offset1:130
	ds_read2_b64 v[202:205], v225 offset0:160 offset1:162
	ds_read2_b64 v[206:209], v226 offset0:192 offset1:194
	ds_read2_b64 v[210:213], v227 offset0:224 offset1:226
	ds_read2_b64 v[220:223], v224 offset0:132 offset1:134
	v_max3_f32 v0, v195, v0, v2
	v_sub_f32 v4, v97, v0
	v_sub_f32 v3, v96, v0
	v_sub_f32 v5, v100, v0
	v_sub_f32_e32 v2, v195, v0
	v_exp_f32_e32 v8, v4
	v_sub_f32 v4, v98, v0
	v_exp_f32_e32 v3, v3
	v_exp_f32_e32 v9, v4
	v_sub_f32 v4, v99, v0
	v_exp_f32_e32 v11, v5
	v_exp_f32_e32 v10, v4
	v_add_f32 v4, v1, v3
	v_sub_f32 v5, v101, v0
	v_exp_f32_e32 v2, v2
	v_add_f32 v4, v4, v8
	v_exp_f32_e32 v12, v5
	v_add_f32 v4, v4, v9
	v_sub_f32 v5, v102, v0
	v_cvt_pk_bf16_f32 v8, v3, v8
	v_add_f32 v4, v4, v10
	v_exp_f32_e32 v13, v5
	v_add_f32 v4, v4, v11
	v_sub_f32 v5, v103, v0
	v_add_f32 v4, v4, v12
	v_exp_f32_e32 v14, v5
	v_add_f32 v4, v4, v13
	v_cvt_pk_bf16_f32 v9, v9, v10
	v_add_f32 v96, v4, v14
	v_sub_f32 v4, v104, v0
	v_exp_f32_e32 v97, v4
	v_sub_f32 v4, v105, v0
	v_cvt_pk_bf16_f32 v10, v11, v12
	v_exp_f32_e32 v98, v4
	v_sub_f32 v4, v106, v0
	v_cvt_pk_bf16_f32 v11, v13, v14
	v_exp_f32_e32 v99, v4
	v_sub_f32 v4, v107, v0
	v_exp_f32_e32 v100, v4
	v_sub_f32 v4, v108, v0
	v_mul_f32 v64, v64, v2
	v_mul_f32 v65, v65, v2
	v_mul_f32 v66, v66, v2
	v_mul_f32 v67, v67, v2
	v_mul_f32 v68, v68, v2
	s_nop 0
	v_exp_f32_e32 v101, v4
	v_sub_f32 v4, v109, v0
	v_mul_f32 v69, v69, v2
	v_mul_f32 v70, v70, v2
	v_mul_f32 v71, v71, v2
	v_mul_f32 v72, v72, v2
	v_mul_f32 v73, v73, v2
	s_nop 0
	v_exp_f32_e32 v102, v4
	v_sub_f32 v4, v110, v0
	v_mul_f32 v74, v74, v2
	v_mul_f32 v75, v75, v2
	v_mul_f32 v76, v76, v2
	v_mul_f32 v77, v77, v2
	v_mul_f32 v78, v78, v2
	s_nop 0
	v_exp_f32_e32 v103, v4
	v_mul_f32 v79, v79, v2
	s_waitcnt lgkmcnt(4)
	v_mfma_f32_32x32x16_bf16 v[64:79], v[196:199], v[8:11], v[64:79]
	ds_read2_b64 v[196:199], v225 offset0:164 offset1:166
	v_mul_f32 v48, v48, v2
	v_mul_f32 v49, v49, v2
	v_mul_f32 v50, v50, v2
	v_mul_f32 v51, v51, v2
	v_mul_f32 v52, v52, v2
	v_mul_f32 v53, v53, v2
	v_mul_f32 v54, v54, v2
	v_mul_f32 v55, v55, v2
	v_mul_f32 v56, v56, v2
	v_mul_f32 v57, v57, v2
	v_mul_f32 v58, v58, v2
	v_mul_f32 v59, v59, v2
	v_mul_f32 v60, v60, v2
	v_mul_f32 v61, v61, v2
	v_mul_f32 v62, v62, v2
	v_mul_f32 v63, v63, v2
	s_waitcnt lgkmcnt(4)
	v_mfma_f32_32x32x16_bf16 v[48:63], v[202:205], v[8:11], v[48:63]
	ds_read2_b64 v[202:205], v226 offset0:196 offset1:198
	v_mul_f32 v32, v32, v2
	v_mul_f32 v33, v33, v2
	v_mul_f32 v34, v34, v2
	v_mul_f32 v35, v35, v2
	v_mul_f32 v36, v36, v2
	v_mul_f32 v37, v37, v2
	v_mul_f32 v38, v38, v2
	v_mul_f32 v39, v39, v2
	v_mul_f32 v40, v40, v2
	v_mul_f32 v41, v41, v2
	v_mul_f32 v42, v42, v2
	v_mul_f32 v43, v43, v2
	v_mul_f32 v44, v44, v2
	v_mul_f32 v45, v45, v2
	v_mul_f32 v46, v46, v2
	v_mul_f32 v47, v47, v2
	v_mul_f32 v16, v16, v2
	v_mul_f32 v17, v17, v2
	v_mul_f32 v18, v18, v2
	v_mul_f32 v19, v19, v2
	v_mul_f32 v20, v20, v2
	s_waitcnt lgkmcnt(4)
	v_mfma_f32_32x32x16_bf16 v[32:47], v[206:209], v[8:11], v[32:47]
	ds_read2_b64 v[206:209], v227 offset0:228 offset1:230
	v_mul_f32 v21, v21, v2
	v_mul_f32 v22, v22, v2
	v_mul_f32 v23, v23, v2
	v_mul_f32 v24, v24, v2
	v_mul_f32 v25, v25, v2
	v_mul_f32 v26, v26, v2
	v_mul_f32 v27, v27, v2
	v_mul_f32 v28, v28, v2
	v_mul_f32 v29, v29, v2
	v_mul_f32 v30, v30, v2
	v_mul_f32 v31, v31, v2
	v_mov_b32_e32 v195, v0
	s_waitcnt lgkmcnt(4)
	v_mfma_f32_32x32x16_bf16 v[16:31], v[210:213], v[8:11], v[16:31]
	ds_read2_b64 v[210:213], v224 offset0:136 offset1:138
	v_sub_f32 v8, v111, v0
	v_cvt_pk_bf16_f32 v9, v99, v100
	v_exp_f32_e32 v107, v8
	v_cvt_pk_bf16_f32 v8, v97, v98
	v_cvt_pk_bf16_f32 v10, v101, v102
	v_cvt_pk_bf16_f32 v11, v103, v107
	s_nop 0
	s_waitcnt lgkmcnt(4)
	v_mfma_f32_32x32x16_bf16 v[64:79], v[220:223], v[8:11], v[64:79]
	ds_read2_b64 v[220:223], v225 offset0:168 offset1:170
	v_add_f32 v4, v96, v97
	s_nop 0
	v_add_f32 v4, v4, v98
	s_nop 0
	v_add_f32 v4, v4, v99
	s_nop 0
	v_add_f32 v96, v4, v100
	v_sub_f32 v4, v80, v0
	s_waitcnt lgkmcnt(4)
	v_mfma_f32_32x32x16_bf16 v[48:63], v[196:199], v[8:11], v[48:63]
	ds_read2_b64 v[196:199], v226 offset0:200 offset1:202
	v_exp_f32_e32 v80, v4
	v_sub_f32 v12, v81, v0
	s_nop 0
	v_exp_f32_e32 v81, v12
	v_sub_f32 v12, v82, v0
	s_nop 0
	v_exp_f32_e32 v82, v12
	v_sub_f32 v12, v83, v0
	s_waitcnt lgkmcnt(4)
	v_mfma_f32_32x32x16_bf16 v[32:47], v[202:205], v[8:11], v[32:47]
	ds_read2_b64 v[202:205], v227 offset0:232 offset1:234
	v_exp_f32_e32 v83, v12
	v_sub_f32 v4, v84, v0
	s_nop 0
	v_exp_f32_e32 v84, v4
	v_sub_f32 v4, v85, v0
	s_nop 0
	v_exp_f32_e32 v85, v4
	v_sub_f32 v4, v86, v0
	s_waitcnt lgkmcnt(4)
	v_mfma_f32_32x32x16_bf16 v[16:31], v[206:209], v[8:11], v[16:31]
	ds_read2_b64 v[206:209], v224 offset0:140 offset1:142
	v_exp_f32_e32 v86, v4
	v_sub_f32 v8, v87, v0
	v_exp_f32_e32 v87, v8
	v_cvt_pk_bf16_f32 v8, v80, v81
	v_cvt_pk_bf16_f32 v9, v82, v83
	v_cvt_pk_bf16_f32 v10, v84, v85
	v_cvt_pk_bf16_f32 v11, v86, v87
	s_nop 0
	s_waitcnt lgkmcnt(4)
	v_mfma_f32_32x32x16_bf16 v[64:79], v[210:213], v[8:11], v[64:79]
	ds_read2_b64 v[210:213], v225 offset0:172 offset1:174
	v_add_f32 v4, v96, v101
	s_nop 0
	v_add_f32 v4, v4, v102
	s_nop 0
	v_add_f32 v4, v4, v103
	s_nop 0
	v_add_f32 v96, v4, v107
	v_sub_f32 v4, v88, v0
	s_waitcnt lgkmcnt(4)
	v_mfma_f32_32x32x16_bf16 v[48:63], v[220:223], v[8:11], v[48:63]
	ds_read2_b64 v[220:223], v226 offset0:204 offset1:206
	v_exp_f32_e32 v88, v4
	v_sub_f32 v12, v89, v0
	s_nop 0
	v_exp_f32_e32 v89, v12
	v_sub_f32 v12, v90, v0
	s_nop 0
	v_exp_f32_e32 v90, v12
	v_sub_f32 v12, v91, v0
	s_waitcnt lgkmcnt(4)
	v_mfma_f32_32x32x16_bf16 v[32:47], v[196:199], v[8:11], v[32:47]
	ds_read2_b64 v[196:199], v227 offset0:236 offset1:238
	v_exp_f32_e32 v91, v12
	v_sub_f32 v4, v92, v0
	s_nop 0
	v_exp_f32_e32 v92, v4
	v_sub_f32 v4, v93, v0
	s_nop 0
	v_exp_f32_e32 v93, v4
	v_sub_f32 v4, v94, v0
	s_waitcnt lgkmcnt(4)
	v_mfma_f32_32x32x16_bf16 v[16:31], v[202:205], v[8:11], v[16:31]
	v_exp_f32_e32 v94, v4
	v_sub_f32 v8, v95, v0
	v_cvt_pk_bf16_f32 v9, v90, v91
	v_exp_f32_e32 v95, v8
	v_cvt_pk_bf16_f32 v8, v88, v89
	v_cvt_pk_bf16_f32 v10, v92, v93
	v_add_f32 v3, v96, v80
	v_cvt_pk_bf16_f32 v11, v94, v95
	v_add_f32 v3, v3, v81
	s_nop 0
	v_add_f32 v3, v3, v82
	s_waitcnt lgkmcnt(3)
	v_mfma_f32_32x32x16_bf16 v[64:79], v[206:209], v[8:11], v[64:79]
	v_add_f32 v3, v3, v83
	s_nop 0
	v_add_f32 v3, v3, v84
	s_nop 0
	v_add_f32 v3, v3, v85
	s_waitcnt lgkmcnt(2)
	v_mfma_f32_32x32x16_bf16 v[48:63], v[210:213], v[8:11], v[48:63]
	v_add_f32 v3, v3, v86
	s_nop 0
	v_add_f32 v3, v3, v87
	s_nop 0
	v_add_f32 v3, v3, v88
	s_nop 0
	v_add_f32 v3, v3, v89
	s_waitcnt lgkmcnt(1)
	v_mfma_f32_32x32x16_bf16 v[32:47], v[220:223], v[8:11], v[32:47]
	v_add_f32 v3, v3, v90
	s_nop 0
	v_add_f32 v3, v3, v91
	s_nop 0
	v_add_f32 v3, v3, v92
	s_nop 0
	v_add_f32 v3, v3, v93
	s_waitcnt lgkmcnt(0)
	v_mfma_f32_32x32x16_bf16 v[16:31], v[196:199], v[8:11], v[16:31]
	v_add_f32 v3, v3, v94
	s_nop 0
	v_add_f32 v3, v3, v95
	s_nop 0
	v_fmac_f32_e32 v3, v184, v2
	v_mov_b32_e32 v184, v3
	s_branch .LBB0_555

.LBB0_598:
	s_and_saveexec_b64 s[24:25], s[6:7]
	s_cbranch_execz .LBB0_587
	ds_read_b128 v[194:197], v185
	ds_read_b128 v[202:205], v185 offset:32
	ds_read_b128 v[206:209], v185 offset:64
	ds_read_b128 v[210:213], v185 offset:96
	ds_read_b128 v[220:223], v185 offset:128
	ds_read_b128 v[224:227], v185 offset:160
	ds_read_b128 v[2:5], v185 offset:192
	ds_read_b128 v[6:9], v185 offset:224
	s_waitcnt lgkmcnt(7)
	v_mfma_f32_32x32x16_bf16 v[96:111], v[194:197], v[148:151], 0
	ds_read_b128 v[194:197], v185 offset:256
	s_waitcnt lgkmcnt(7)
	v_mfma_f32_32x32x16_bf16 v[96:111], v[202:205], v[144:147], v[96:111]
	ds_read_b128 v[202:205], v185 offset:288
	s_waitcnt lgkmcnt(7)
	v_mfma_f32_32x32x16_bf16 v[96:111], v[206:209], v[140:143], v[96:111]
	ds_read_b128 v[206:209], v185 offset:10752
	s_waitcnt lgkmcnt(7)
	v_mfma_f32_32x32x16_bf16 v[96:111], v[210:213], v[136:139], v[96:111]
	ds_read_b128 v[210:213], v185 offset:10784
	s_waitcnt lgkmcnt(7)
	v_mfma_f32_32x32x16_bf16 v[96:111], v[220:223], v[132:135], v[96:111]
	ds_read_b128 v[220:223], v185 offset:10816
	s_waitcnt lgkmcnt(7)
	v_mfma_f32_32x32x16_bf16 v[96:111], v[224:227], v[128:131], v[96:111]
	ds_read_b128 v[224:227], v185 offset:10848
	s_waitcnt lgkmcnt(7)
	v_mfma_f32_32x32x16_bf16 v[96:111], v[2:5], v[124:127], v[96:111]
	ds_read_b128 v[2:5], v185 offset:10880
	s_waitcnt lgkmcnt(7)
	v_mfma_f32_32x32x16_bf16 v[96:111], v[6:9], v[120:123], v[96:111]
	ds_read_b128 v[6:9], v185 offset:10912
	s_waitcnt lgkmcnt(7)
	v_mfma_f32_32x32x16_bf16 v[96:111], v[194:197], v[116:119], v[96:111]
	ds_read_b128 v[194:197], v185 offset:10944
	s_waitcnt lgkmcnt(7)
	v_mfma_f32_32x32x16_bf16 v[96:111], v[202:205], v[112:115], v[96:111]
	ds_read_b128 v[202:205], v185 offset:10976
	s_waitcnt lgkmcnt(7)
	v_mfma_f32_32x32x16_bf16 v[80:95], v[206:209], v[148:151], 0
	ds_read_b128 v[206:209], v185 offset:11008
	s_waitcnt lgkmcnt(7)
	v_mfma_f32_32x32x16_bf16 v[80:95], v[210:213], v[144:147], v[80:95]
	ds_read_b128 v[210:213], v185 offset:11040
	s_waitcnt lgkmcnt(7)
	v_mfma_f32_32x32x16_bf16 v[80:95], v[220:223], v[140:143], v[80:95]
	s_waitcnt lgkmcnt(6)
	v_mfma_f32_32x32x16_bf16 v[80:95], v[224:227], v[136:139], v[80:95]
	s_waitcnt lgkmcnt(5)
	v_mfma_f32_32x32x16_bf16 v[80:95], v[2:5], v[132:135], v[80:95]
	s_waitcnt lgkmcnt(4)
	v_mfma_f32_32x32x16_bf16 v[80:95], v[6:9], v[128:131], v[80:95]
	s_waitcnt lgkmcnt(3)
	v_mfma_f32_32x32x16_bf16 v[80:95], v[194:197], v[124:127], v[80:95]
	v_max_f32_e32 v0, v97, v97
	v_max_f32_e32 v10, v96, v96
	v_max_f32_e32 v0, v10, v0
	v_max3_f32 v0, v0, v98, v99
	v_max3_f32 v0, v0, v100, v101
	v_max3_f32 v0, v0, v102, v103
	v_max3_f32 v0, v0, v104, v105
	v_max3_f32 v0, v0, v106, v107
	v_max3_f32 v0, v0, v108, v109
	v_max3_f32 v0, v0, v110, v111
	v_and_b32_e32 v3, 64, v218
	v_xor_b32_e32 v2, 32, v218
	v_add_u32_e32 v3, 64, v3
	v_cmp_lt_i32_e32 vcc, v2, v3
	s_nop 1
	v_cndmask_b32_e32 v2, v218, v2, vcc
	s_waitcnt lgkmcnt(2)
	v_mfma_f32_32x32x16_bf16 v[80:95], v[202:205], v[120:123], v[80:95]
	s_waitcnt lgkmcnt(1)
	v_mfma_f32_32x32x16_bf16 v[80:95], v[206:209], v[116:119], v[80:95]
	s_waitcnt lgkmcnt(0)
	v_mfma_f32_32x32x16_bf16 v[80:95], v[210:213], v[112:115], v[80:95]
	v_lshlrev_b32_e32 v2, 2, v2
	s_nop 10
	v_max3_f32 v0, v0, v80, v81
	v_max3_f32 v0, v0, v82, v83
	v_max3_f32 v0, v0, v84, v85
	v_max3_f32 v0, v0, v86, v87
	v_max3_f32 v0, v0, v88, v89
	v_max3_f32 v0, v0, v90, v91
	v_max3_f32 v0, v0, v92, v93
	v_max3_f32 v0, v0, v94, v95
	v_mov_b32_e32 v2, v0
	s_nop 1
	v_permlane32_swap_b32_e32 v2, v0
	s_nop 1
	v_add_u32_e32 v224, 0x5000, v191
	v_add_u32_e32 v225, 0x6000, v191
	v_add_u32_e32 v226, 0x7000, v191
	v_add_u32_e32 v227, 0x8000, v191
	ds_read2_b64 v[194:197], v224 offset0:128 offset1:130
	ds_read2_b64 v[202:205], v225 offset0:160 offset1:162
	ds_read2_b64 v[206:209], v226 offset0:192 offset1:194
	ds_read2_b64 v[210:213], v227 offset0:224 offset1:226
	ds_read2_b64 v[220:223], v224 offset0:132 offset1:134
	v_max3_f32 v0, v192, v0, v2
	v_sub_f32 v4, v97, v0
	v_sub_f32 v3, v96, v0
	v_sub_f32 v5, v100, v0
	v_sub_f32_e32 v2, v192, v0
	v_exp_f32_e32 v8, v4
	v_sub_f32 v4, v98, v0
	v_exp_f32_e32 v3, v3
	v_exp_f32_e32 v9, v4
	v_sub_f32 v4, v99, v0
	v_exp_f32_e32 v11, v5
	v_exp_f32_e32 v10, v4
	v_add_f32 v4, v1, v3
	v_sub_f32 v5, v101, v0
	v_exp_f32_e32 v2, v2
	v_add_f32 v4, v4, v8
	v_exp_f32_e32 v12, v5
	v_add_f32 v4, v4, v9
	v_sub_f32 v5, v102, v0
	v_cvt_pk_bf16_f32 v8, v3, v8
	v_add_f32 v4, v4, v10
	v_exp_f32_e32 v13, v5
	v_add_f32 v4, v4, v11
	v_sub_f32 v5, v103, v0
	v_add_f32 v4, v4, v12
	v_exp_f32_e32 v14, v5
	v_add_f32 v4, v4, v13
	v_cvt_pk_bf16_f32 v9, v9, v10
	v_add_f32 v96, v4, v14
	v_sub_f32 v4, v104, v0
	v_exp_f32_e32 v97, v4
	v_sub_f32 v4, v105, v0
	v_cvt_pk_bf16_f32 v10, v11, v12
	v_exp_f32_e32 v98, v4
	v_sub_f32 v4, v106, v0
	v_cvt_pk_bf16_f32 v11, v13, v14
	v_exp_f32_e32 v99, v4
	v_sub_f32 v4, v107, v0
	v_exp_f32_e32 v100, v4
	v_sub_f32 v4, v108, v0
	v_mul_f32 v64, v64, v2
	v_mul_f32 v65, v65, v2
	v_mul_f32 v66, v66, v2
	v_mul_f32 v67, v67, v2
	v_mul_f32 v68, v68, v2
	s_nop 0
	v_exp_f32_e32 v101, v4
	v_sub_f32 v4, v109, v0
	v_mul_f32 v69, v69, v2
	v_mul_f32 v70, v70, v2
	v_mul_f32 v71, v71, v2
	v_mul_f32 v72, v72, v2
	v_mul_f32 v73, v73, v2
	s_nop 0
	v_exp_f32_e32 v102, v4
	v_sub_f32 v4, v110, v0
	v_mul_f32 v74, v74, v2
	v_mul_f32 v75, v75, v2
	v_mul_f32 v76, v76, v2
	v_mul_f32 v77, v77, v2
	v_mul_f32 v78, v78, v2
	s_nop 0
	v_exp_f32_e32 v103, v4
	v_mul_f32 v79, v79, v2
	s_waitcnt lgkmcnt(4)
	v_mfma_f32_32x32x16_bf16 v[64:79], v[194:197], v[8:11], v[64:79]
	ds_read2_b64 v[194:197], v225 offset0:164 offset1:166
	v_mul_f32 v48, v48, v2
	v_mul_f32 v49, v49, v2
	v_mul_f32 v50, v50, v2
	v_mul_f32 v51, v51, v2
	v_mul_f32 v52, v52, v2
	v_mul_f32 v53, v53, v2
	v_mul_f32 v54, v54, v2
	v_mul_f32 v55, v55, v2
	v_mul_f32 v56, v56, v2
	v_mul_f32 v57, v57, v2
	v_mul_f32 v58, v58, v2
	v_mul_f32 v59, v59, v2
	v_mul_f32 v60, v60, v2
	v_mul_f32 v61, v61, v2
	v_mul_f32 v62, v62, v2
	v_mul_f32 v63, v63, v2
	s_waitcnt lgkmcnt(4)
	v_mfma_f32_32x32x16_bf16 v[48:63], v[202:205], v[8:11], v[48:63]
	ds_read2_b64 v[202:205], v226 offset0:196 offset1:198
	v_mul_f32 v32, v32, v2
	v_mul_f32 v33, v33, v2
	v_mul_f32 v34, v34, v2
	v_mul_f32 v35, v35, v2
	v_mul_f32 v36, v36, v2
	v_mul_f32 v37, v37, v2
	v_mul_f32 v38, v38, v2
	v_mul_f32 v39, v39, v2
	v_mul_f32 v40, v40, v2
	v_mul_f32 v41, v41, v2
	v_mul_f32 v42, v42, v2
	v_mul_f32 v43, v43, v2
	v_mul_f32 v44, v44, v2
	v_mul_f32 v45, v45, v2
	v_mul_f32 v46, v46, v2
	v_mul_f32 v47, v47, v2
	v_mul_f32 v16, v16, v2
	v_mul_f32 v17, v17, v2
	v_mul_f32 v18, v18, v2
	v_mul_f32 v19, v19, v2
	v_mul_f32 v20, v20, v2
	s_waitcnt lgkmcnt(4)
	v_mfma_f32_32x32x16_bf16 v[32:47], v[206:209], v[8:11], v[32:47]
	ds_read2_b64 v[206:209], v227 offset0:228 offset1:230
	v_mul_f32 v21, v21, v2
	v_mul_f32 v22, v22, v2
	v_mul_f32 v23, v23, v2
	v_mul_f32 v24, v24, v2
	v_mul_f32 v25, v25, v2
	v_mul_f32 v26, v26, v2
	v_mul_f32 v27, v27, v2
	v_mul_f32 v28, v28, v2
	v_mul_f32 v29, v29, v2
	v_mul_f32 v30, v30, v2
	v_mul_f32 v31, v31, v2
	v_mov_b32_e32 v192, v0
	s_waitcnt lgkmcnt(4)
	v_mfma_f32_32x32x16_bf16 v[16:31], v[210:213], v[8:11], v[16:31]
	ds_read2_b64 v[210:213], v224 offset0:136 offset1:138
	v_sub_f32 v8, v111, v0
	v_cvt_pk_bf16_f32 v9, v99, v100
	v_exp_f32_e32 v107, v8
	v_cvt_pk_bf16_f32 v8, v97, v98
	v_cvt_pk_bf16_f32 v10, v101, v102
	v_cvt_pk_bf16_f32 v11, v103, v107
	s_nop 0
	s_waitcnt lgkmcnt(4)
	v_mfma_f32_32x32x16_bf16 v[64:79], v[220:223], v[8:11], v[64:79]
	ds_read2_b64 v[220:223], v225 offset0:168 offset1:170
	v_add_f32 v4, v96, v97
	s_nop 0
	v_add_f32 v4, v4, v98
	s_nop 0
	v_add_f32 v4, v4, v99
	s_nop 0
	v_add_f32 v96, v4, v100
	v_sub_f32 v4, v80, v0
	s_waitcnt lgkmcnt(4)
	v_mfma_f32_32x32x16_bf16 v[48:63], v[194:197], v[8:11], v[48:63]
	ds_read2_b64 v[194:197], v226 offset0:200 offset1:202
	v_exp_f32_e32 v80, v4
	v_sub_f32 v12, v81, v0
	s_nop 0
	v_exp_f32_e32 v81, v12
	v_sub_f32 v12, v82, v0
	s_nop 0
	v_exp_f32_e32 v82, v12
	v_sub_f32 v12, v83, v0
	s_waitcnt lgkmcnt(4)
	v_mfma_f32_32x32x16_bf16 v[32:47], v[202:205], v[8:11], v[32:47]
	ds_read2_b64 v[202:205], v227 offset0:232 offset1:234
	v_exp_f32_e32 v83, v12
	v_sub_f32 v4, v84, v0
	s_nop 0
	v_exp_f32_e32 v84, v4
	v_sub_f32 v4, v85, v0
	s_nop 0
	v_exp_f32_e32 v85, v4
	v_sub_f32 v4, v86, v0
	s_waitcnt lgkmcnt(4)
	v_mfma_f32_32x32x16_bf16 v[16:31], v[206:209], v[8:11], v[16:31]
	ds_read2_b64 v[206:209], v224 offset0:140 offset1:142
	v_exp_f32_e32 v86, v4
	v_sub_f32 v8, v87, v0
	v_exp_f32_e32 v87, v8
	v_cvt_pk_bf16_f32 v8, v80, v81
	v_cvt_pk_bf16_f32 v9, v82, v83
	v_cvt_pk_bf16_f32 v10, v84, v85
	v_cvt_pk_bf16_f32 v11, v86, v87
	s_nop 0
	s_waitcnt lgkmcnt(4)
	v_mfma_f32_32x32x16_bf16 v[64:79], v[210:213], v[8:11], v[64:79]
	ds_read2_b64 v[210:213], v225 offset0:172 offset1:174
	v_add_f32 v4, v96, v101
	s_nop 0
	v_add_f32 v4, v4, v102
	s_nop 0
	v_add_f32 v4, v4, v103
	s_nop 0
	v_add_f32 v96, v4, v107
	v_sub_f32 v4, v88, v0
	s_waitcnt lgkmcnt(4)
	v_mfma_f32_32x32x16_bf16 v[48:63], v[220:223], v[8:11], v[48:63]
	ds_read2_b64 v[220:223], v226 offset0:204 offset1:206
	v_exp_f32_e32 v88, v4
	v_sub_f32 v12, v89, v0
	s_nop 0
	v_exp_f32_e32 v89, v12
	v_sub_f32 v12, v90, v0
	s_nop 0
	v_exp_f32_e32 v90, v12
	v_sub_f32 v12, v91, v0
	s_waitcnt lgkmcnt(4)
	v_mfma_f32_32x32x16_bf16 v[32:47], v[194:197], v[8:11], v[32:47]
	ds_read2_b64 v[194:197], v227 offset0:236 offset1:238
	v_exp_f32_e32 v91, v12
	v_sub_f32 v4, v92, v0
	s_nop 0
	v_exp_f32_e32 v92, v4
	v_sub_f32 v4, v93, v0
	s_nop 0
	v_exp_f32_e32 v93, v4
	v_sub_f32 v4, v94, v0
	s_waitcnt lgkmcnt(4)
	v_mfma_f32_32x32x16_bf16 v[16:31], v[202:205], v[8:11], v[16:31]
	v_exp_f32_e32 v94, v4
	v_sub_f32 v8, v95, v0
	v_cvt_pk_bf16_f32 v9, v90, v91
	v_exp_f32_e32 v95, v8
	v_cvt_pk_bf16_f32 v8, v88, v89
	v_cvt_pk_bf16_f32 v10, v92, v93
	v_add_f32 v3, v96, v80
	v_cvt_pk_bf16_f32 v11, v94, v95
	v_add_f32 v3, v3, v81
	s_nop 0
	v_add_f32 v3, v3, v82
	s_waitcnt lgkmcnt(3)
	v_mfma_f32_32x32x16_bf16 v[64:79], v[206:209], v[8:11], v[64:79]
	v_add_f32 v3, v3, v83
	s_nop 0
	v_add_f32 v3, v3, v84
	s_nop 0
	v_add_f32 v3, v3, v85
	s_waitcnt lgkmcnt(2)
	v_mfma_f32_32x32x16_bf16 v[48:63], v[210:213], v[8:11], v[48:63]
	v_add_f32 v3, v3, v86
	s_nop 0
	v_add_f32 v3, v3, v87
	s_nop 0
	v_add_f32 v3, v3, v88
	s_nop 0
	v_add_f32 v3, v3, v89
	s_waitcnt lgkmcnt(1)
	v_mfma_f32_32x32x16_bf16 v[32:47], v[220:223], v[8:11], v[32:47]
	v_add_f32 v3, v3, v90
	s_nop 0
	v_add_f32 v3, v3, v91
	s_nop 0
	v_add_f32 v3, v3, v92
	s_nop 0
	v_add_f32 v3, v3, v93
	s_waitcnt lgkmcnt(0)
	v_mfma_f32_32x32x16_bf16 v[16:31], v[194:197], v[8:11], v[16:31]
	v_add_f32 v3, v3, v94
	s_nop 0
	v_add_f32 v3, v3, v95
	s_nop 0
	v_fmac_f32_e32 v3, v184, v2
	v_mov_b32_e32 v184, v3
	s_branch .LBB0_587

.LBB0_1215:
	s_and_saveexec_b64 s[70:71], s[8:9]
	s_cbranch_execz .LBB0_1202
	ds_read_b128 v[220:223], v245
	ds_read_b128 v[224:227], v245 offset:32
	ds_read_b128 v[2:5], v245 offset:64
	ds_read_b128 v[6:9], v245 offset:96
	s_waitcnt lgkmcnt(3)
	v_mfma_f32_32x32x16_bf16 v[96:111], v[220:223], v[172:175], 0
	ds_read_b128 v[220:223], v245 offset:128
	s_waitcnt lgkmcnt(3)
	v_mfma_f32_32x32x16_bf16 v[96:111], v[224:227], v[168:171], v[96:111]
	ds_read_b128 v[224:227], v245 offset:160
	s_waitcnt lgkmcnt(3)
	v_mfma_f32_32x32x16_bf16 v[96:111], v[2:5], v[164:167], v[96:111]
	ds_read_b128 v[2:5], v245 offset:192
	s_waitcnt lgkmcnt(3)
	v_mfma_f32_32x32x16_bf16 v[96:111], v[6:9], v[160:163], v[96:111]
	ds_read_b128 v[6:9], v245 offset:224
	s_waitcnt lgkmcnt(3)
	v_mfma_f32_32x32x16_bf16 v[96:111], v[220:223], v[156:159], v[96:111]
	ds_read_b128 v[220:223], v245 offset:256
	s_waitcnt lgkmcnt(3)
	v_mfma_f32_32x32x16_bf16 v[96:111], v[224:227], v[152:155], v[96:111]
	ds_read_b128 v[224:227], v245 offset:288
	s_waitcnt lgkmcnt(3)
	v_mfma_f32_32x32x16_bf16 v[96:111], v[2:5], v[148:151], v[96:111]
	ds_read_b128 v[2:5], v245 offset:320
	s_waitcnt lgkmcnt(3)
	v_mfma_f32_32x32x16_bf16 v[96:111], v[6:9], v[144:147], v[96:111]
	ds_read_b128 v[6:9], v245 offset:352
	s_waitcnt lgkmcnt(3)
	v_mfma_f32_32x32x16_bf16 v[96:111], v[220:223], v[140:143], v[96:111]
	ds_read_b128 v[220:223], v245 offset:384
	s_waitcnt lgkmcnt(3)
	v_mfma_f32_32x32x16_bf16 v[96:111], v[224:227], v[136:139], v[96:111]
	ds_read_b128 v[224:227], v245 offset:416
	s_waitcnt lgkmcnt(3)
	v_mfma_f32_32x32x16_bf16 v[96:111], v[2:5], v[132:135], v[96:111]
	ds_read_b128 v[2:5], v245 offset:448
	s_waitcnt lgkmcnt(3)
	v_mfma_f32_32x32x16_bf16 v[96:111], v[6:9], v[128:131], v[96:111]
	ds_read_b128 v[6:9], v245 offset:480
	s_waitcnt lgkmcnt(3)
	v_mfma_f32_32x32x16_bf16 v[96:111], v[220:223], v[124:127], v[96:111]
	ds_read_b128 v[220:223], v245 offset:16896
	s_waitcnt lgkmcnt(3)
	v_mfma_f32_32x32x16_bf16 v[96:111], v[224:227], v[120:123], v[96:111]
	ds_read_b128 v[224:227], v245 offset:16928
	s_waitcnt lgkmcnt(3)
	v_mfma_f32_32x32x16_bf16 v[96:111], v[2:5], v[116:119], v[96:111]
	ds_read_b128 v[2:5], v245 offset:16960
	s_waitcnt lgkmcnt(3)
	v_mfma_f32_32x32x16_bf16 v[96:111], v[6:9], v[112:115], v[96:111]
	ds_read_b128 v[6:9], v245 offset:16992
	s_waitcnt lgkmcnt(3)
	v_mfma_f32_32x32x16_bf16 v[80:95], v[220:223], v[172:175], 0
	ds_read_b128 v[220:223], v245 offset:17024
	s_waitcnt lgkmcnt(3)
	v_mfma_f32_32x32x16_bf16 v[80:95], v[224:227], v[168:171], v[80:95]
	ds_read_b128 v[224:227], v245 offset:17056
	s_waitcnt lgkmcnt(3)
	v_mfma_f32_32x32x16_bf16 v[80:95], v[2:5], v[164:167], v[80:95]
	ds_read_b128 v[2:5], v245 offset:17088
	s_waitcnt lgkmcnt(3)
	v_mfma_f32_32x32x16_bf16 v[80:95], v[6:9], v[160:163], v[80:95]
	ds_read_b128 v[6:9], v245 offset:17120
	s_waitcnt lgkmcnt(3)
	v_mfma_f32_32x32x16_bf16 v[80:95], v[220:223], v[156:159], v[80:95]
	ds_read_b128 v[220:223], v245 offset:17152
	s_waitcnt lgkmcnt(3)
	v_mfma_f32_32x32x16_bf16 v[80:95], v[224:227], v[152:155], v[80:95]
	ds_read_b128 v[224:227], v245 offset:17184
	s_waitcnt lgkmcnt(3)
	v_mfma_f32_32x32x16_bf16 v[80:95], v[2:5], v[148:151], v[80:95]
	ds_read_b128 v[2:5], v245 offset:17216
	s_waitcnt lgkmcnt(3)
	v_mfma_f32_32x32x16_bf16 v[80:95], v[6:9], v[144:147], v[80:95]
	ds_read_b128 v[6:9], v245 offset:17248
	s_waitcnt lgkmcnt(3)
	v_mfma_f32_32x32x16_bf16 v[80:95], v[220:223], v[140:143], v[80:95]
	ds_read_b128 v[220:223], v245 offset:17280
	s_waitcnt lgkmcnt(3)
	v_mfma_f32_32x32x16_bf16 v[80:95], v[224:227], v[136:139], v[80:95]
	ds_read_b128 v[224:227], v245 offset:17312
	s_waitcnt lgkmcnt(3)
	v_mfma_f32_32x32x16_bf16 v[80:95], v[2:5], v[132:135], v[80:95]
	ds_read_b128 v[2:5], v245 offset:17344
	s_waitcnt lgkmcnt(3)
	v_mfma_f32_32x32x16_bf16 v[80:95], v[6:9], v[128:131], v[80:95]
	ds_read_b128 v[6:9], v245 offset:17376
	s_waitcnt lgkmcnt(3)
	v_mfma_f32_32x32x16_bf16 v[80:95], v[220:223], v[124:127], v[80:95]
	s_waitcnt lgkmcnt(2)
	v_mfma_f32_32x32x16_bf16 v[80:95], v[224:227], v[120:123], v[80:95]
	s_waitcnt lgkmcnt(1)
	v_mfma_f32_32x32x16_bf16 v[80:95], v[2:5], v[116:119], v[80:95]
	s_waitcnt lgkmcnt(0)
	v_mfma_f32_32x32x16_bf16 v[80:95], v[6:9], v[112:115], v[80:95]
	v_max_f32_e32 v0, v97, v97
	v_max_f32_e32 v10, v96, v96
	v_max_f32_e32 v0, v10, v0
	v_max3_f32 v0, v0, v98, v99
	v_max3_f32 v0, v0, v100, v101
	v_max3_f32 v0, v0, v102, v103
	v_max3_f32 v0, v0, v104, v105
	v_max3_f32 v0, v0, v106, v107
	v_max3_f32 v0, v0, v108, v109
	v_max3_f32 v0, v0, v110, v111
	v_and_b32_e32 v3, 64, v218
	v_xor_b32_e32 v2, 32, v218
	v_add_u32_e32 v3, 64, v3
	v_cmp_lt_i32_e32 vcc, v2, v3
	s_nop 1
	v_cndmask_b32_e32 v2, v218, v2, vcc
	v_lshlrev_b32_e32 v2, 2, v2
	s_nop 10
	v_max3_f32 v0, v0, v80, v81
	v_max3_f32 v0, v0, v82, v83
	v_max3_f32 v0, v0, v84, v85
	v_max3_f32 v0, v0, v86, v87
	v_max3_f32 v0, v0, v88, v89
	v_max3_f32 v0, v0, v90, v91
	v_max3_f32 v0, v0, v92, v93
	v_max3_f32 v0, v0, v94, v95
	v_mov_b32_e32 v2, v0
	s_nop 1
	v_permlane32_swap_b32_e32 v2, v0
	s_nop 1
	v_max3_f32 v0, v236, v0, v2
	v_sub_f32 v4, v97, v0
	v_sub_f32 v3, v96, v0
	v_sub_f32 v5, v100, v0
	v_sub_f32_e32 v2, v236, v0
	v_exp_f32_e32 v8, v4
	v_sub_f32 v4, v98, v0
	v_exp_f32_e32 v3, v3
	v_exp_f32_e32 v9, v4
	v_sub_f32 v4, v99, v0
	v_exp_f32_e32 v11, v5
	v_exp_f32_e32 v10, v4
	v_add_f32 v4, v1, v3
	v_sub_f32 v5, v101, v0
	v_exp_f32_e32 v2, v2
	v_add_f32 v4, v4, v8
	v_exp_f32_e32 v12, v5
	v_add_f32 v4, v4, v9
	v_sub_f32 v5, v102, v0
	v_cvt_pk_bf16_f32 v8, v3, v8
	v_add_f32 v4, v4, v10
	v_exp_f32_e32 v13, v5
	v_add_f32 v4, v4, v11
	v_sub_f32 v5, v103, v0
	v_add_u32_e32 v3, 0x9000, v219
	v_add_f32 v4, v4, v12
	v_exp_f32_e32 v14, v5
	v_add_f32 v4, v4, v13
	v_cvt_pk_bf16_f32 v9, v9, v10
	v_add_f32 v96, v4, v14
	v_sub_f32 v4, v104, v0
	v_add_u32_e32 v104, 0x8000, v219
	v_exp_f32_e32 v97, v4
	v_sub_f32 v4, v105, v0
	v_cvt_pk_bf16_f32 v10, v11, v12
	v_exp_f32_e32 v98, v4
	v_sub_f32 v4, v106, v0
	v_cvt_pk_bf16_f32 v11, v13, v14
	v_exp_f32_e32 v99, v4
	v_sub_f32 v4, v107, v0
	ds_read2_b64 v[12:15], v3 offset0:160 offset1:162
	v_exp_f32_e32 v100, v4
	v_sub_f32 v4, v108, v0
	v_mul_f32 v64, v64, v2
	v_mul_f32 v65, v65, v2
	v_mul_f32 v66, v66, v2
	v_mul_f32 v67, v67, v2
	v_mul_f32 v68, v68, v2
	s_nop 0
	v_exp_f32_e32 v101, v4
	v_sub_f32 v4, v109, v0
	v_mul_f32 v69, v69, v2
	v_mul_f32 v70, v70, v2
	v_mul_f32 v71, v71, v2
	v_mul_f32 v72, v72, v2
	v_mul_f32 v73, v73, v2
	s_nop 0
	v_exp_f32_e32 v102, v4
	v_sub_f32 v4, v110, v0
	v_mul_f32 v74, v74, v2
	v_mul_f32 v75, v75, v2
	v_mul_f32 v76, v76, v2
	v_mul_f32 v77, v77, v2
	v_mul_f32 v78, v78, v2
	s_nop 0
	v_exp_f32_e32 v103, v4
	ds_read2_b64 v[4:7], v104 offset0:128 offset1:130
	v_mul_f32 v79, v79, v2
	v_add_u32_e32 v105, 0xa000, v219
	s_waitcnt lgkmcnt(0)
	v_mfma_f32_32x32x16_bf16 v[64:79], v[4:7], v[8:11], v[64:79]
	ds_read2_b64 v[4:7], v105 offset0:192 offset1:194
	v_mul_f32 v48, v48, v2
	v_mul_f32 v49, v49, v2
	v_mul_f32 v50, v50, v2
	v_mul_f32 v51, v51, v2
	v_mul_f32 v52, v52, v2
	v_mul_f32 v53, v53, v2
	v_mul_f32 v54, v54, v2
	v_mul_f32 v55, v55, v2
	v_mul_f32 v56, v56, v2
	v_mul_f32 v57, v57, v2
	v_mul_f32 v58, v58, v2
	v_mul_f32 v59, v59, v2
	v_mul_f32 v60, v60, v2
	v_mul_f32 v61, v61, v2
	v_mul_f32 v62, v62, v2
	v_mul_f32 v63, v63, v2
	v_add_u32_e32 v106, 0xb000, v219
	v_mfma_f32_32x32x16_bf16 v[48:63], v[12:15], v[8:11], v[48:63]
	ds_read2_b64 v[12:15], v106 offset0:224 offset1:226
	v_mul_f32 v32, v32, v2
	v_mul_f32 v33, v33, v2
	v_mul_f32 v34, v34, v2
	v_mul_f32 v35, v35, v2
	v_mul_f32 v36, v36, v2
	v_mul_f32 v37, v37, v2
	v_mul_f32 v38, v38, v2
	v_mul_f32 v39, v39, v2
	v_mul_f32 v40, v40, v2
	v_mul_f32 v41, v41, v2
	v_mul_f32 v42, v42, v2
	v_mul_f32 v43, v43, v2
	v_mul_f32 v44, v44, v2
	v_mul_f32 v45, v45, v2
	v_mul_f32 v46, v46, v2
	v_mul_f32 v47, v47, v2
	v_mul_f32 v16, v16, v2
	v_mul_f32 v17, v17, v2
	v_mul_f32 v18, v18, v2
	v_mul_f32 v19, v19, v2
	v_mul_f32 v20, v20, v2
	s_waitcnt lgkmcnt(1)
	v_mfma_f32_32x32x16_bf16 v[32:47], v[4:7], v[8:11], v[32:47]
	ds_read2_b64 v[4:7], v104 offset0:132 offset1:134
	v_mul_f32 v21, v21, v2
	v_mul_f32 v22, v22, v2
	v_mul_f32 v23, v23, v2
	v_mul_f32 v24, v24, v2
	v_mul_f32 v25, v25, v2
	v_mul_f32 v26, v26, v2
	v_mul_f32 v27, v27, v2
	v_mul_f32 v28, v28, v2
	v_mul_f32 v29, v29, v2
	v_mul_f32 v30, v30, v2
	v_mul_f32 v31, v31, v2
	v_mov_b32_e32 v236, v0
	s_waitcnt lgkmcnt(1)
	v_mfma_f32_32x32x16_bf16 v[16:31], v[12:15], v[8:11], v[16:31]
	v_sub_f32 v8, v111, v0
	v_cvt_pk_bf16_f32 v9, v99, v100
	v_exp_f32_e32 v107, v8
	v_cvt_pk_bf16_f32 v8, v97, v98
	v_cvt_pk_bf16_f32 v10, v101, v102
	ds_read2_b64 v[12:15], v3 offset0:164 offset1:166
	v_cvt_pk_bf16_f32 v11, v103, v107
	s_waitcnt lgkmcnt(1)
	s_nop 0
	v_mfma_f32_32x32x16_bf16 v[64:79], v[4:7], v[8:11], v[64:79]
	v_add_f32 v4, v96, v97
	s_nop 0
	v_add_f32 v4, v4, v98
	s_nop 0
	v_add_f32 v4, v4, v99
	s_nop 0
	v_add_f32 v96, v4, v100
	v_sub_f32 v4, v80, v0
	s_waitcnt lgkmcnt(0)
	v_mfma_f32_32x32x16_bf16 v[48:63], v[12:15], v[8:11], v[48:63]
	v_exp_f32_e32 v80, v4
	ds_read2_b64 v[4:7], v105 offset0:196 offset1:198
	v_sub_f32 v12, v81, v0
	s_nop 0
	v_exp_f32_e32 v81, v12
	v_sub_f32 v12, v82, v0
	s_nop 0
	v_exp_f32_e32 v82, v12
	v_sub_f32 v12, v83, v0
	s_waitcnt lgkmcnt(0)
	v_mfma_f32_32x32x16_bf16 v[32:47], v[4:7], v[8:11], v[32:47]
	v_exp_f32_e32 v83, v12
	ds_read2_b64 v[12:15], v106 offset0:228 offset1:230
	v_sub_f32 v4, v84, v0
	s_nop 0
	v_exp_f32_e32 v84, v4
	v_sub_f32 v4, v85, v0
	s_nop 0
	v_exp_f32_e32 v85, v4
	v_sub_f32 v4, v86, v0
	s_waitcnt lgkmcnt(0)
	v_mfma_f32_32x32x16_bf16 v[16:31], v[12:15], v[8:11], v[16:31]
	v_exp_f32_e32 v86, v4
	ds_read2_b64 v[4:7], v104 offset0:136 offset1:138
	v_sub_f32 v8, v87, v0
	ds_read2_b64 v[12:15], v3 offset0:168 offset1:170
	v_exp_f32_e32 v87, v8
	v_cvt_pk_bf16_f32 v8, v80, v81
	v_cvt_pk_bf16_f32 v9, v82, v83
	v_cvt_pk_bf16_f32 v10, v84, v85
	v_cvt_pk_bf16_f32 v11, v86, v87
	s_waitcnt lgkmcnt(1)
	s_nop 0
	v_mfma_f32_32x32x16_bf16 v[64:79], v[4:7], v[8:11], v[64:79]
	v_add_f32 v4, v96, v101
	s_nop 0
	v_add_f32 v4, v4, v102
	s_nop 0
	v_add_f32 v4, v4, v103
	s_nop 0
	v_add_f32 v96, v4, v107
	v_sub_f32 v4, v88, v0
	s_waitcnt lgkmcnt(0)
	v_mfma_f32_32x32x16_bf16 v[48:63], v[12:15], v[8:11], v[48:63]
	v_exp_f32_e32 v88, v4
	ds_read2_b64 v[4:7], v105 offset0:200 offset1:202
	v_sub_f32 v12, v89, v0
	s_nop 0
	v_exp_f32_e32 v89, v12
	v_sub_f32 v12, v90, v0
	s_nop 0
	v_exp_f32_e32 v90, v12
	v_sub_f32 v12, v91, v0
	s_waitcnt lgkmcnt(0)
	v_mfma_f32_32x32x16_bf16 v[32:47], v[4:7], v[8:11], v[32:47]
	v_exp_f32_e32 v91, v12
	ds_read2_b64 v[12:15], v106 offset0:232 offset1:234
	v_sub_f32 v4, v92, v0
	s_nop 0
	v_exp_f32_e32 v92, v4
	v_sub_f32 v4, v93, v0
	s_nop 0
	v_exp_f32_e32 v93, v4
	v_sub_f32 v4, v94, v0
	s_waitcnt lgkmcnt(0)
	v_mfma_f32_32x32x16_bf16 v[16:31], v[12:15], v[8:11], v[16:31]
	v_exp_f32_e32 v94, v4
	ds_read2_b64 v[4:7], v104 offset0:140 offset1:142
	ds_read2_b64 v[12:15], v3 offset0:172 offset1:174
	v_sub_f32 v8, v95, v0
	v_cvt_pk_bf16_f32 v9, v90, v91
	v_exp_f32_e32 v95, v8
	v_cvt_pk_bf16_f32 v8, v88, v89
	v_cvt_pk_bf16_f32 v10, v92, v93
	v_add_f32 v3, v96, v80
	v_cvt_pk_bf16_f32 v11, v94, v95
	v_add_f32 v3, v3, v81
	s_nop 0
	v_add_f32 v3, v3, v82
	s_waitcnt lgkmcnt(1)
	v_mfma_f32_32x32x16_bf16 v[64:79], v[4:7], v[8:11], v[64:79]
	ds_read2_b64 v[4:7], v105 offset0:204 offset1:206
	v_add_f32 v3, v3, v83
	s_nop 0
	v_add_f32 v3, v3, v84
	s_nop 0
	v_add_f32 v3, v3, v85
	s_waitcnt lgkmcnt(1)
	v_mfma_f32_32x32x16_bf16 v[48:63], v[12:15], v[8:11], v[48:63]
	ds_read2_b64 v[12:15], v106 offset0:236 offset1:238
	v_add_f32 v3, v3, v86
	s_nop 0
	v_add_f32 v3, v3, v87
	s_nop 0
	v_add_f32 v3, v3, v88
	s_nop 0
	v_add_f32 v3, v3, v89
	s_waitcnt lgkmcnt(1)
	v_mfma_f32_32x32x16_bf16 v[32:47], v[4:7], v[8:11], v[32:47]
	v_add_f32 v3, v3, v90
	s_nop 0
	v_add_f32 v3, v3, v91
	s_nop 0
	v_add_f32 v3, v3, v92
	s_nop 0
	v_add_f32 v3, v3, v93
	s_waitcnt lgkmcnt(0)
	v_mfma_f32_32x32x16_bf16 v[16:31], v[12:15], v[8:11], v[16:31]
	v_add_f32 v3, v3, v94
	s_nop 0
	v_add_f32 v3, v3, v95
	s_nop 0
	v_fmac_f32_e32 v3, v246, v2
	v_mov_b32_e32 v246, v3
	s_branch .LBB0_1202
